# v17: v12 with the hand-written attention instruction stream shifted by 4 bytes (byte-phase test, code placement lever)
# speedup vs baseline: 1.0157x; 1.0029x over previous
.Lmy_attn:
	s_nop 0
	s_mov_b64 exec, -1
	s_mov_b32 s51, m0
	s_add_u32 s8, s12, 0x5800000
	s_addc_u32 s9, s13, 0
	s_add_u32 s20, s12, 0x7000000
	s_addc_u32 s21, s13, 0
	s_add_u32 s34, s12, 0x7800000
	s_addc_u32 s35, s13, 0
	v_and_b32_e32 v0, 63, v210
	v_readfirstlane_b32 s2, v210
	s_nop 3
	s_lshr_b32 s2, s2, 6
	s_lshl_b32 s31, s2, 10
	s_add_i32 s48, s31, 0x2000
	s_add_i32 s49, s31, 0x4000
	s_add_i32 s40, s31, 24576
	s_add_i32 s54, s31, 32768
	s_add_i32 s55, s31, 40960
	v_lshrrev_b32_e32 v1, 5, v0
	v_and_b32_e32 v2, 31, v0
	v_lshlrev_b32_e32 v3, 4, v2
	v_lshl_or_b32 v209, v1, 10, v3
	v_bfe_u32 v3, v0, 4, 1
	v_lshlrev_b32_e32 v3, 5, v3
	v_and_b32_e32 v4, 3, v0
	v_lshl_add_u32 v3, v4, 3, v3
	v_bfe_u32 v4, v0, 2, 2
	v_lshl_add_u32 v4, v1, 2, v4
	v_lshl_add_u32 v3, v4, 6, v3
	v_add_u32_e32 v190, 24576, v3
	s_lshl_b32 s6, s2, 4
	v_lshl_add_u32 v254, v0, 9, s6
	s_and_b32 s6, s2, 3
	s_lshl_b32 s6, s6, 13
	s_lshr_b32 s7, s2, 2
	s_lshl_b32 s7, s7, 6
	s_add_i32 s6, s6, s7
	v_lshrrev_b32_e32 v3, 2, v0
	v_and_b32_e32 v4, 3, v0
	v_lshlrev_b32_e32 v4, 4, v4
	v_lshl_add_u32 v3, v3, 9, v4
	v_add_u32_e32 v255, s6, v3
	v_and_b32_e32 v3, 15, v0
	v_bfe_u32 v4, v0, 4, 1
	v_cmp_eq_u32_e32 vcc, v3, v4
	v_mov_b32_e32 v5, 0x3f803f80
	s_nop 1
	v_cndmask_b32_e32 v226, 0, v5, vcc
	v_cndmask_b32_e32 v227, 0, v5, vcc
	v_cndmask_b32_e32 v228, 0, v5, vcc
	v_cndmask_b32_e32 v229, 0, v5, vcc
	v_readlane_b32 s41, v253, 2
	s_nop 3
	s_and_b32 s6, s41, 31
	s_bfe_u32 s7, s41, 0x30005
	s_lshr_b32 s13, s7, 2
	s_and_b32 s7, s7, 3
	s_mul_i32 s30, s7, 3
	s_lshl_b32 s13, s13, 13
	s_lshl_b32 s6, s6, 8
	s_add_i32 s6, s6, s13
	s_lshl_b32 s12, s2, 5
	s_add_i32 s6, s6, s12
	s_lshl_b32 s12, s13, 9
	s_lshl_b32 s7, s7, 7
	s_add_i32 s12, s12, s7
	s_add_u32 s36, s20, s12
	s_addc_u32 s37, s21, 0
	s_add_u32 s38, s34, s12
	s_addc_u32 s39, s35, 0
	s_lshl_b32 s30, s30, 7
	s_lshl_b32 s12, s6, 11
	s_add_i32 s12, s12, s30
	s_add_u32 s46, s14, s12
	s_addc_u32 s47, s15, 0
	s_mul_i32 s12, s6, 0x600
	s_add_i32 s12, s12, s30
	s_add_u32 s12, s8, s12
	s_addc_u32 s13, s9, 0
	s_mov_b64 s[44:45], s[12:13]
	v_and_b32_e32 v93, 31, v210
	v_bfe_u32 v94, v210, 5, 1
	v_mul_u32_u24_e32 v93, 0x600, v93
	v_lshl_add_u32 v92, v94, 4, v93
	global_load_dwordx4 v[64:67], v92, s[44:45] offset:0
	global_load_dwordx4 v[68:71], v92, s[44:45] offset:32
	global_load_dwordx4 v[72:75], v92, s[44:45] offset:64
	global_load_dwordx4 v[76:79], v92, s[44:45] offset:96
	global_load_dwordx4 v[80:83], v92, s[44:45] offset:128
	global_load_dwordx4 v[84:87], v92, s[44:45] offset:160
	global_load_dwordx4 v[88:91], v92, s[44:45] offset:192
	global_load_dwordx4 v[230:233], v92, s[44:45] offset:224
	s_mov_b32 m0, s31
	s_nop 0
	global_load_lds_dwordx4 v254, s[36:37]
	s_mov_b32 m0, s40
	s_nop 0
	global_load_lds_dwordx4 v255, s[38:39]
	s_add_u32 s42, s36, 0x8000
	s_addc_u32 s43, s37, 0
	s_mov_b32 m0, s48
	s_nop 0
	global_load_lds_dwordx4 v254, s[42:43]
	s_add_u32 s42, s36, 0x10000
	s_addc_u32 s43, s37, 0
	s_mov_b32 m0, s49
	s_nop 0
	global_load_lds_dwordx4 v254, s[42:43]
	s_add_u32 s42, s36, 0x18000
	s_addc_u32 s43, s37, 0
	s_add_u32 s44, s38, 0x8000
	s_addc_u32 s45, s39, 0
	s_mov_b32 m0, s54
	s_nop 0
	global_load_lds_dwordx4 v255, s[44:45]
	s_add_u32 s44, s44, 0x8000
	s_addc_u32 s45, s45, 0
	s_movk_i32 s57, 20
	v_mov_b32_e32 v0, 0
	v_mov_b32_e32 v1, 0
	v_mov_b32_e32 v2, 0
	v_mov_b32_e32 v3, 0
	v_mov_b32_e32 v4, 0
	v_mov_b32_e32 v5, 0
	v_mov_b32_e32 v6, 0
	v_mov_b32_e32 v7, 0
	v_mov_b32_e32 v8, 0
	v_mov_b32_e32 v9, 0
	v_mov_b32_e32 v10, 0
	v_mov_b32_e32 v11, 0
	v_mov_b32_e32 v12, 0
	v_mov_b32_e32 v13, 0
	v_mov_b32_e32 v14, 0
	v_mov_b32_e32 v15, 0
	v_mov_b32_e32 v16, 0
	v_mov_b32_e32 v17, 0
	v_mov_b32_e32 v18, 0
	v_mov_b32_e32 v19, 0
	v_mov_b32_e32 v20, 0
	v_mov_b32_e32 v21, 0
	v_mov_b32_e32 v22, 0
	v_mov_b32_e32 v23, 0
	v_mov_b32_e32 v24, 0
	v_mov_b32_e32 v25, 0
	v_mov_b32_e32 v26, 0
	v_mov_b32_e32 v27, 0
	v_mov_b32_e32 v28, 0
	v_mov_b32_e32 v29, 0
	v_mov_b32_e32 v30, 0
	v_mov_b32_e32 v31, 0
	v_mov_b32_e32 v204, 0
	v_mov_b32_e32 v205, 0
	v_mov_b32_e32 v206, 0
	v_mov_b32_e32 v207, 0
	v_mov_b32_e32 v32, 0
	v_mov_b32_e32 v33, 0
	v_mov_b32_e32 v34, 0
	v_mov_b32_e32 v35, 0
	v_mov_b32_e32 v36, 0
	v_mov_b32_e32 v37, 0
	v_mov_b32_e32 v38, 0
	v_mov_b32_e32 v39, 0
	v_mov_b32_e32 v40, 0
	v_mov_b32_e32 v41, 0
	v_mov_b32_e32 v42, 0
	v_mov_b32_e32 v43, 0
	v_mov_b32_e32 v44, 0
	v_mov_b32_e32 v45, 0
	v_mov_b32_e32 v46, 0
	v_mov_b32_e32 v47, 0
	v_mov_b32_e32 v48, 0
	v_mov_b32_e32 v49, 0
	v_mov_b32_e32 v50, 0
	v_mov_b32_e32 v51, 0
	v_mov_b32_e32 v52, 0
	v_mov_b32_e32 v53, 0
	v_mov_b32_e32 v54, 0
	v_mov_b32_e32 v55, 0
	v_mov_b32_e32 v56, 0
	v_mov_b32_e32 v57, 0
	v_mov_b32_e32 v58, 0
	v_mov_b32_e32 v59, 0
	v_mov_b32_e32 v60, 0
	v_mov_b32_e32 v61, 0
	v_mov_b32_e32 v62, 0
	v_mov_b32_e32 v63, 0
	v_mov_b32_e32 v222, 0
	v_mov_b32_e32 v223, 0
	v_mov_b32_e32 v224, 0
	v_mov_b32_e32 v225, 0
	s_waitcnt vmcnt(1)
	s_barrier
	ds_read_b128 v[92:95], v209 offset:0
	ds_read_b128 v[96:99], v209 offset:512
	ds_read_b128 v[100:103], v209 offset:2048
	ds_read_b128 v[104:107], v209 offset:2560
	ds_read_b128 v[108:111], v209 offset:4096
	ds_read_b128 v[112:115], v209 offset:4608
	ds_read_b128 v[116:119], v209 offset:6144
	ds_read_b128 v[120:123], v209 offset:6656
	s_waitcnt lgkmcnt(0)
	s_barrier
